# w_in epilogue plain path (rv/rg/dv tiles) rewritten by hand: silu evaluated only for the rg tiles instead of for all three types, stat loads hoisted, packed f32 ops
# speedup vs baseline: 1.0139x; 1.0038x over previous
; __device__ __forceinline__ float ss_scale(const u64* ss, int row) { return __builtin_amdgcn_rsqf((float)ss[row] * (1.f / 4294967296.f / 1024.f) + EPS); }
; __device__ __forceinline__ unsigned pkbf(float lo, float hi) { typedef __bf16 bf2_t __attribute__((ext_vector_type(2))); f32x2 v = {lo, hi}; bf2_t b = __builtin_convertvector(v, bf2_t); return __builtin_bit_cast(unsigned, b); }
; __device__ __forceinline__ float silu_f(float g) { return g * __builtin_amdgcn_rcpf(1.f + __builtin_amdgcn_exp2f(-g * LOG2E)); }
;     __device__ __forceinline__ void operator()(const f32x4 (&acc)[2][2][4][2], const pg8::Unit& u, int wr, int wc, int fr, int fq) const {
;     ...
;         } else {
;             const bool act = (type == 3);
; #pragma unroll
;             for (int ai = 0; ai < 2; ++ai)
; #pragma unroll
;                 for (int m = 0; m < 4; ++m) {
;                     const int row = row0 + ai * 128 + m * 16;
;                     const float s = ss_scale(ss, row);
;                     bf16* op = P + (size_t)row * NIN + cbase + wc * 32 + 8 * fq;
; #pragma unroll
;                     for (int bj = 0; bj < 2; ++bj) {
;                         float v[8];
; #pragma unroll
;                         for (int n = 0; n < 2; ++n)
; #pragma unroll
;                             for (int i = 0; i < 4; ++i) { const float x = acc[ai][bj][m][n][i] * s; v[4 * n + i] = act ? silu_f(x) : x; }
;                         u32x4 w; w.x = pkbf(v[0], v[1]); w.y = pkbf(v[2], v[3]); w.z = pkbf(v[4], v[5]); w.w = pkbf(v[6], v[7]);
;                         *(u32x4*)(op + bj * 128) = w;
;                     }
;                 }
.LBB0_443:
	s_and_b32 s1, s0, 0x7ffffffe
	s_cmp_lg_u32 s1, 4
	v_lshlrev_b32_e32 v136, 1, v138
	s_cbranch_scc0 .LBB0_445
	v_ashrrev_i32_e32 v153, 31, v152
	v_lshl_add_u64 v[154:155], v[152:153], 3, s[14:15]
	global_load_dwordx2 v[190:191], v[154:155], off
	global_load_dwordx2 v[192:193], v[154:155], off offset:128
	global_load_dwordx2 v[194:195], v[154:155], off offset:256
	global_load_dwordx2 v[196:197], v[154:155], off offset:384
	global_load_dwordx2 v[200:201], v[154:155], off offset:1024
	global_load_dwordx2 v[202:203], v[154:155], off offset:1152
	global_load_dwordx2 v[204:205], v[154:155], off offset:1280
	global_load_dwordx2 v[206:207], v[154:155], off offset:1408
	s_ashr_i32 s31, s30, 31
	s_mov_b32 s21, s9
	v_mov_b64_e32 v[156:157], s[12:13]
	v_mad_i64_i32 v[158:159], s[34:35], v152, s73, v[156:157]
	v_mov_b32_e32 v166, 0xbfb8aa3b
	v_mov_b32_e32 v168, 1.0
	v_mov_b32_e32 v169, 1.0
	s_nop 1
	s_lshl_b64 s[34:35], s[30:31], 1
	v_lshl_add_u64 v[162:163], v[158:159], 0, s[34:35]
	v_lshl_add_u64 v[162:163], v[162:163], 0, s[20:21]
	v_lshl_add_u64 v[162:163], v[162:163], 0, v[136:137]
	s_mov_b32 s101, 0
	s_cmp_eq_u32 s0, 3
	s_cbranch_scc1 .Lpl_silu_l0
	s_waitcnt vmcnt(7)
	v_cvt_f32_u32_e32 v170, v191
	v_cvt_f32_u32_e32 v171, v190
	v_fmamk_f32 v170, v170, 0x4f800000, v171
	v_fmamk_f32 v170, v170, 0x2a800000, v179
	v_rsq_f32_e32 v164, v170
	s_nop 0
	v_pk_mul_f32 v[124:125], v[124:125], v[164:165] op_sel_hi:[1,0]
	v_pk_mul_f32 v[126:127], v[126:127], v[164:165] op_sel_hi:[1,0]
	v_pk_mul_f32 v[120:121], v[120:121], v[164:165] op_sel_hi:[1,0]
	v_pk_mul_f32 v[122:123], v[122:123], v[164:165] op_sel_hi:[1,0]
	v_pk_mul_f32 v[116:117], v[116:117], v[164:165] op_sel_hi:[1,0]
	v_pk_mul_f32 v[118:119], v[118:119], v[164:165] op_sel_hi:[1,0]
	v_pk_mul_f32 v[112:113], v[112:113], v[164:165] op_sel_hi:[1,0]
	v_pk_mul_f32 v[114:115], v[114:115], v[164:165] op_sel_hi:[1,0]
	v_cvt_pk_bf16_f32 v124, v124, v125
	v_cvt_pk_bf16_f32 v125, v126, v127
	v_cvt_pk_bf16_f32 v126, v120, v121
	v_cvt_pk_bf16_f32 v127, v122, v123
	v_cvt_pk_bf16_f32 v116, v116, v117
	v_cvt_pk_bf16_f32 v117, v118, v119
	v_cvt_pk_bf16_f32 v118, v112, v113
	v_cvt_pk_bf16_f32 v119, v114, v115
	global_store_dwordx4 v[162:163], v[124:127], off
	global_store_dwordx4 v[162:163], v[116:119], off offset:256
	s_waitcnt vmcnt(8)
	v_cvt_f32_u32_e32 v170, v193
	v_cvt_f32_u32_e32 v171, v192
	v_fmamk_f32 v170, v170, 0x4f800000, v171
	v_fmamk_f32 v170, v170, 0x2a800000, v179
	v_rsq_f32_e32 v164, v170
	s_nop 0
	v_pk_mul_f32 v[108:109], v[108:109], v[164:165] op_sel_hi:[1,0]
	v_pk_mul_f32 v[110:111], v[110:111], v[164:165] op_sel_hi:[1,0]
	v_pk_mul_f32 v[104:105], v[104:105], v[164:165] op_sel_hi:[1,0]
	v_pk_mul_f32 v[106:107], v[106:107], v[164:165] op_sel_hi:[1,0]
	v_pk_mul_f32 v[100:101], v[100:101], v[164:165] op_sel_hi:[1,0]
	v_pk_mul_f32 v[102:103], v[102:103], v[164:165] op_sel_hi:[1,0]
	v_pk_mul_f32 v[96:97], v[96:97], v[164:165] op_sel_hi:[1,0]
	v_pk_mul_f32 v[98:99], v[98:99], v[164:165] op_sel_hi:[1,0]
	v_cvt_pk_bf16_f32 v108, v108, v109
	v_cvt_pk_bf16_f32 v109, v110, v111
	v_cvt_pk_bf16_f32 v110, v104, v105
	v_cvt_pk_bf16_f32 v111, v106, v107
	v_cvt_pk_bf16_f32 v100, v100, v101
	v_cvt_pk_bf16_f32 v101, v102, v103
	v_cvt_pk_bf16_f32 v102, v96, v97
	v_cvt_pk_bf16_f32 v103, v98, v99
	s_mov_b32 s100, 0x1c000
	v_lshl_add_u64 v[172:173], v[162:163], 0, s[100:101]
	global_store_dwordx4 v[172:173], v[108:111], off
	global_store_dwordx4 v[172:173], v[100:103], off offset:256
	s_waitcnt vmcnt(9)
	v_cvt_f32_u32_e32 v170, v195
	v_cvt_f32_u32_e32 v171, v194
	v_fmamk_f32 v170, v170, 0x4f800000, v171
	v_fmamk_f32 v170, v170, 0x2a800000, v179
	v_rsq_f32_e32 v164, v170
	s_nop 0
	v_pk_mul_f32 v[92:93], v[92:93], v[164:165] op_sel_hi:[1,0]
	v_pk_mul_f32 v[94:95], v[94:95], v[164:165] op_sel_hi:[1,0]
	v_pk_mul_f32 v[88:89], v[88:89], v[164:165] op_sel_hi:[1,0]
	v_pk_mul_f32 v[90:91], v[90:91], v[164:165] op_sel_hi:[1,0]
	v_pk_mul_f32 v[84:85], v[84:85], v[164:165] op_sel_hi:[1,0]
	v_pk_mul_f32 v[86:87], v[86:87], v[164:165] op_sel_hi:[1,0]
	v_pk_mul_f32 v[80:81], v[80:81], v[164:165] op_sel_hi:[1,0]
	v_pk_mul_f32 v[82:83], v[82:83], v[164:165] op_sel_hi:[1,0]
	v_cvt_pk_bf16_f32 v92, v92, v93
	v_cvt_pk_bf16_f32 v93, v94, v95
	v_cvt_pk_bf16_f32 v94, v88, v89
	v_cvt_pk_bf16_f32 v95, v90, v91
	v_cvt_pk_bf16_f32 v84, v84, v85
	v_cvt_pk_bf16_f32 v85, v86, v87
	v_cvt_pk_bf16_f32 v86, v80, v81
	v_cvt_pk_bf16_f32 v87, v82, v83
	s_mov_b32 s100, 0x38000
	v_lshl_add_u64 v[172:173], v[162:163], 0, s[100:101]
	global_store_dwordx4 v[172:173], v[92:95], off
	global_store_dwordx4 v[172:173], v[84:87], off offset:256
	s_waitcnt vmcnt(10)
	v_cvt_f32_u32_e32 v170, v197
	v_cvt_f32_u32_e32 v171, v196
	v_fmamk_f32 v170, v170, 0x4f800000, v171
	v_fmamk_f32 v170, v170, 0x2a800000, v179
	v_rsq_f32_e32 v164, v170
	s_nop 0
	v_pk_mul_f32 v[76:77], v[76:77], v[164:165] op_sel_hi:[1,0]
	v_pk_mul_f32 v[78:79], v[78:79], v[164:165] op_sel_hi:[1,0]
	v_pk_mul_f32 v[72:73], v[72:73], v[164:165] op_sel_hi:[1,0]
	v_pk_mul_f32 v[74:75], v[74:75], v[164:165] op_sel_hi:[1,0]
	v_pk_mul_f32 v[68:69], v[68:69], v[164:165] op_sel_hi:[1,0]
	v_pk_mul_f32 v[70:71], v[70:71], v[164:165] op_sel_hi:[1,0]
	v_pk_mul_f32 v[64:65], v[64:65], v[164:165] op_sel_hi:[1,0]
	v_pk_mul_f32 v[66:67], v[66:67], v[164:165] op_sel_hi:[1,0]
	v_cvt_pk_bf16_f32 v76, v76, v77
	v_cvt_pk_bf16_f32 v77, v78, v79
	v_cvt_pk_bf16_f32 v78, v72, v73
	v_cvt_pk_bf16_f32 v79, v74, v75
	v_cvt_pk_bf16_f32 v68, v68, v69
	v_cvt_pk_bf16_f32 v69, v70, v71
	v_cvt_pk_bf16_f32 v70, v64, v65
	v_cvt_pk_bf16_f32 v71, v66, v67
	s_mov_b32 s100, 0x54000
	v_lshl_add_u64 v[172:173], v[162:163], 0, s[100:101]
	global_store_dwordx4 v[172:173], v[76:79], off
	global_store_dwordx4 v[172:173], v[68:71], off offset:256
	s_waitcnt vmcnt(11)
; __device__ __forceinline__ float ss_scale(const u64* ss, int row) { return __builtin_amdgcn_rsqf((float)ss[row] * (1.f / 4294967296.f / 1024.f) + EPS); }
; __device__ __forceinline__ unsigned pkbf(float lo, float hi) { typedef __bf16 bf2_t __attribute__((ext_vector_type(2))); f32x2 v = {lo, hi}; bf2_t b = __builtin_convertvector(v, bf2_t); return __builtin_bit_cast(unsigned, b); }
; __device__ __forceinline__ float silu_f(float g) { return g * __builtin_amdgcn_rcpf(1.f + __builtin_amdgcn_exp2f(-g * LOG2E)); }
;     __device__ __forceinline__ void operator()(const f32x4 (&acc)[2][2][4][2], const pg8::Unit& u, int wr, int wc, int fr, int fq) const {
;     ...
;         } else {
;             const bool act = (type == 3);
; #pragma unroll
;             for (int ai = 0; ai < 2; ++ai)
; #pragma unroll
;                 for (int m = 0; m < 4; ++m) {
;                     const int row = row0 + ai * 128 + m * 16;
;                     const float s = ss_scale(ss, row);
;                     bf16* op = P + (size_t)row * NIN + cbase + wc * 32 + 8 * fq;
; #pragma unroll
;                     for (int bj = 0; bj < 2; ++bj) {
;                         float v[8];
; #pragma unroll
;                         for (int n = 0; n < 2; ++n)
; #pragma unroll
;                             for (int i = 0; i < 4; ++i) { const float x = acc[ai][bj][m][n][i] * s; v[4 * n + i] = act ? silu_f(x) : x; }
;                         u32x4 w; w.x = pkbf(v[0], v[1]); w.y = pkbf(v[2], v[3]); w.z = pkbf(v[4], v[5]); w.w = pkbf(v[6], v[7]);
;                         *(u32x4*)(op + bj * 128) = w;
;                     }
;                 }
	v_cvt_f32_u32_e32 v170, v201
	v_cvt_f32_u32_e32 v171, v200
	v_fmamk_f32 v170, v170, 0x4f800000, v171
	v_fmamk_f32 v170, v170, 0x2a800000, v179
	v_rsq_f32_e32 v164, v170
	s_nop 0
	v_pk_mul_f32 v[60:61], v[60:61], v[164:165] op_sel_hi:[1,0]
	v_pk_mul_f32 v[62:63], v[62:63], v[164:165] op_sel_hi:[1,0]
	v_pk_mul_f32 v[56:57], v[56:57], v[164:165] op_sel_hi:[1,0]
	v_pk_mul_f32 v[58:59], v[58:59], v[164:165] op_sel_hi:[1,0]
	v_pk_mul_f32 v[52:53], v[52:53], v[164:165] op_sel_hi:[1,0]
	v_pk_mul_f32 v[54:55], v[54:55], v[164:165] op_sel_hi:[1,0]
	v_pk_mul_f32 v[48:49], v[48:49], v[164:165] op_sel_hi:[1,0]
	v_pk_mul_f32 v[50:51], v[50:51], v[164:165] op_sel_hi:[1,0]
	v_cvt_pk_bf16_f32 v60, v60, v61
	v_cvt_pk_bf16_f32 v61, v62, v63
	v_cvt_pk_bf16_f32 v62, v56, v57
	v_cvt_pk_bf16_f32 v63, v58, v59
	v_cvt_pk_bf16_f32 v52, v52, v53
	v_cvt_pk_bf16_f32 v53, v54, v55
	v_cvt_pk_bf16_f32 v54, v48, v49
	v_cvt_pk_bf16_f32 v55, v50, v51
	s_mov_b32 s100, 0xe0000
	v_lshl_add_u64 v[172:173], v[162:163], 0, s[100:101]
	global_store_dwordx4 v[172:173], v[60:63], off
	global_store_dwordx4 v[172:173], v[52:55], off offset:256
	s_waitcnt vmcnt(12)
	v_cvt_f32_u32_e32 v170, v203
	v_cvt_f32_u32_e32 v171, v202
	v_fmamk_f32 v170, v170, 0x4f800000, v171
	v_fmamk_f32 v170, v170, 0x2a800000, v179
	v_rsq_f32_e32 v164, v170
	s_nop 0
	v_pk_mul_f32 v[44:45], v[44:45], v[164:165] op_sel_hi:[1,0]
	v_pk_mul_f32 v[46:47], v[46:47], v[164:165] op_sel_hi:[1,0]
	v_pk_mul_f32 v[40:41], v[40:41], v[164:165] op_sel_hi:[1,0]
	v_pk_mul_f32 v[42:43], v[42:43], v[164:165] op_sel_hi:[1,0]
	v_pk_mul_f32 v[36:37], v[36:37], v[164:165] op_sel_hi:[1,0]
	v_pk_mul_f32 v[38:39], v[38:39], v[164:165] op_sel_hi:[1,0]
	v_pk_mul_f32 v[32:33], v[32:33], v[164:165] op_sel_hi:[1,0]
	v_pk_mul_f32 v[34:35], v[34:35], v[164:165] op_sel_hi:[1,0]
	v_cvt_pk_bf16_f32 v44, v44, v45
	v_cvt_pk_bf16_f32 v45, v46, v47
	v_cvt_pk_bf16_f32 v46, v40, v41
	v_cvt_pk_bf16_f32 v47, v42, v43
	v_cvt_pk_bf16_f32 v36, v36, v37
	v_cvt_pk_bf16_f32 v37, v38, v39
	v_cvt_pk_bf16_f32 v38, v32, v33
	v_cvt_pk_bf16_f32 v39, v34, v35
	s_mov_b32 s100, 0xfc000
	v_lshl_add_u64 v[172:173], v[162:163], 0, s[100:101]
	global_store_dwordx4 v[172:173], v[44:47], off
	global_store_dwordx4 v[172:173], v[36:39], off offset:256
	s_waitcnt vmcnt(13)
	v_cvt_f32_u32_e32 v170, v205
	v_cvt_f32_u32_e32 v171, v204
	v_fmamk_f32 v170, v170, 0x4f800000, v171
	v_fmamk_f32 v170, v170, 0x2a800000, v179
	v_rsq_f32_e32 v164, v170
	s_nop 0
	v_pk_mul_f32 v[28:29], v[28:29], v[164:165] op_sel_hi:[1,0]
	v_pk_mul_f32 v[30:31], v[30:31], v[164:165] op_sel_hi:[1,0]
	v_pk_mul_f32 v[24:25], v[24:25], v[164:165] op_sel_hi:[1,0]
	v_pk_mul_f32 v[26:27], v[26:27], v[164:165] op_sel_hi:[1,0]
	v_pk_mul_f32 v[20:21], v[20:21], v[164:165] op_sel_hi:[1,0]
	v_pk_mul_f32 v[22:23], v[22:23], v[164:165] op_sel_hi:[1,0]
	v_pk_mul_f32 v[16:17], v[16:17], v[164:165] op_sel_hi:[1,0]
	v_pk_mul_f32 v[18:19], v[18:19], v[164:165] op_sel_hi:[1,0]
	v_cvt_pk_bf16_f32 v28, v28, v29
	v_cvt_pk_bf16_f32 v29, v30, v31
	v_cvt_pk_bf16_f32 v30, v24, v25
	v_cvt_pk_bf16_f32 v31, v26, v27
	v_cvt_pk_bf16_f32 v20, v20, v21
	v_cvt_pk_bf16_f32 v21, v22, v23
	v_cvt_pk_bf16_f32 v22, v16, v17
	v_cvt_pk_bf16_f32 v23, v18, v19
	s_mov_b32 s100, 0x118000
	v_lshl_add_u64 v[172:173], v[162:163], 0, s[100:101]
	global_store_dwordx4 v[172:173], v[28:31], off
	global_store_dwordx4 v[172:173], v[20:23], off offset:256
	s_waitcnt vmcnt(14)
	v_cvt_f32_u32_e32 v170, v207
	v_cvt_f32_u32_e32 v171, v206
	v_fmamk_f32 v170, v170, 0x4f800000, v171
	v_fmamk_f32 v170, v170, 0x2a800000, v179
	v_rsq_f32_e32 v164, v170
	s_nop 0
	v_pk_mul_f32 v[12:13], v[12:13], v[164:165] op_sel_hi:[1,0]
	v_pk_mul_f32 v[14:15], v[14:15], v[164:165] op_sel_hi:[1,0]
	v_pk_mul_f32 v[8:9], v[8:9], v[164:165] op_sel_hi:[1,0]
	v_pk_mul_f32 v[10:11], v[10:11], v[164:165] op_sel_hi:[1,0]
	v_pk_mul_f32 v[4:5], v[4:5], v[164:165] op_sel_hi:[1,0]
	v_pk_mul_f32 v[6:7], v[6:7], v[164:165] op_sel_hi:[1,0]
	v_pk_mul_f32 v[0:1], v[0:1], v[164:165] op_sel_hi:[1,0]
	v_pk_mul_f32 v[2:3], v[2:3], v[164:165] op_sel_hi:[1,0]
	v_cvt_pk_bf16_f32 v12, v12, v13
	v_cvt_pk_bf16_f32 v13, v14, v15
	v_cvt_pk_bf16_f32 v14, v8, v9
	v_cvt_pk_bf16_f32 v15, v10, v11
	v_cvt_pk_bf16_f32 v4, v4, v5
	v_cvt_pk_bf16_f32 v5, v6, v7
	v_cvt_pk_bf16_f32 v6, v0, v1
	v_cvt_pk_bf16_f32 v7, v2, v3
	s_mov_b32 s100, 0x134000
	v_lshl_add_u64 v[172:173], v[162:163], 0, s[100:101]
	global_store_dwordx4 v[172:173], v[12:15], off
	global_store_dwordx4 v[172:173], v[4:7], off offset:256
	s_branch .Lpl_end_l0
; __device__ __forceinline__ float ss_scale(const u64* ss, int row) { return __builtin_amdgcn_rsqf((float)ss[row] * (1.f / 4294967296.f / 1024.f) + EPS); }
; __device__ __forceinline__ unsigned pkbf(float lo, float hi) { typedef __bf16 bf2_t __attribute__((ext_vector_type(2))); f32x2 v = {lo, hi}; bf2_t b = __builtin_convertvector(v, bf2_t); return __builtin_bit_cast(unsigned, b); }
; __device__ __forceinline__ float silu_f(float g) { return g * __builtin_amdgcn_rcpf(1.f + __builtin_amdgcn_exp2f(-g * LOG2E)); }
;     __device__ __forceinline__ void operator()(const f32x4 (&acc)[2][2][4][2], const pg8::Unit& u, int wr, int wc, int fr, int fq) const {
;     ...
;         } else {
;             const bool act = (type == 3);
; #pragma unroll
;             for (int ai = 0; ai < 2; ++ai)
; #pragma unroll
;                 for (int m = 0; m < 4; ++m) {
;                     const int row = row0 + ai * 128 + m * 16;
;                     const float s = ss_scale(ss, row);
;                     bf16* op = P + (size_t)row * NIN + cbase + wc * 32 + 8 * fq;
; #pragma unroll
;                     for (int bj = 0; bj < 2; ++bj) {
;                         float v[8];
; #pragma unroll
;                         for (int n = 0; n < 2; ++n)
; #pragma unroll
;                             for (int i = 0; i < 4; ++i) { const float x = acc[ai][bj][m][n][i] * s; v[4 * n + i] = act ? silu_f(x) : x; }
;                         u32x4 w; w.x = pkbf(v[0], v[1]); w.y = pkbf(v[2], v[3]); w.z = pkbf(v[4], v[5]); w.w = pkbf(v[6], v[7]);
;                         *(u32x4*)(op + bj * 128) = w;
;                     }
;                 }
.Lpl_silu_l0:
	s_waitcnt vmcnt(7)
	v_cvt_f32_u32_e32 v170, v191
	v_cvt_f32_u32_e32 v171, v190
	v_fmamk_f32 v170, v170, 0x4f800000, v171
	v_fmamk_f32 v170, v170, 0x2a800000, v179
	v_rsq_f32_e32 v164, v170
	s_nop 0
	v_pk_mul_f32 v[124:125], v[124:125], v[164:165] op_sel_hi:[1,0]
	v_pk_mul_f32 v[126:127], v[126:127], v[164:165] op_sel_hi:[1,0]
	v_pk_mul_f32 v[120:121], v[120:121], v[164:165] op_sel_hi:[1,0]
	v_pk_mul_f32 v[122:123], v[122:123], v[164:165] op_sel_hi:[1,0]
	v_pk_mul_f32 v[116:117], v[116:117], v[164:165] op_sel_hi:[1,0]
	v_pk_mul_f32 v[118:119], v[118:119], v[164:165] op_sel_hi:[1,0]
	v_pk_mul_f32 v[112:113], v[112:113], v[164:165] op_sel_hi:[1,0]
	v_pk_mul_f32 v[114:115], v[114:115], v[164:165] op_sel_hi:[1,0]
	v_pk_mul_f32 v[182:183], v[124:125], v[166:167] op_sel_hi:[1,0]
	v_pk_mul_f32 v[184:185], v[126:127], v[166:167] op_sel_hi:[1,0]
	v_pk_mul_f32 v[186:187], v[120:121], v[166:167] op_sel_hi:[1,0]
	v_pk_mul_f32 v[188:189], v[122:123], v[166:167] op_sel_hi:[1,0]
	v_exp_f32_e32 v182, v182
	v_exp_f32_e32 v183, v183
	v_exp_f32_e32 v184, v184
	v_exp_f32_e32 v185, v185
	v_exp_f32_e32 v186, v186
	v_exp_f32_e32 v187, v187
	v_exp_f32_e32 v188, v188
	v_exp_f32_e32 v189, v189
	v_pk_add_f32 v[182:183], v[182:183], v[168:169]
	v_pk_add_f32 v[184:185], v[184:185], v[168:169]
	v_pk_add_f32 v[186:187], v[186:187], v[168:169]
	v_pk_add_f32 v[188:189], v[188:189], v[168:169]
	v_rcp_f32_e32 v182, v182
	v_rcp_f32_e32 v183, v183
	v_rcp_f32_e32 v184, v184
	v_rcp_f32_e32 v185, v185
	v_rcp_f32_e32 v186, v186
	v_rcp_f32_e32 v187, v187
	v_rcp_f32_e32 v188, v188
	v_rcp_f32_e32 v189, v189
	s_nop 0
	v_pk_mul_f32 v[124:125], v[124:125], v[182:183]
	v_pk_mul_f32 v[126:127], v[126:127], v[184:185]
	v_pk_mul_f32 v[120:121], v[120:121], v[186:187]
	v_pk_mul_f32 v[122:123], v[122:123], v[188:189]
	v_pk_mul_f32 v[182:183], v[116:117], v[166:167] op_sel_hi:[1,0]
	v_pk_mul_f32 v[184:185], v[118:119], v[166:167] op_sel_hi:[1,0]
	v_pk_mul_f32 v[186:187], v[112:113], v[166:167] op_sel_hi:[1,0]
	v_pk_mul_f32 v[188:189], v[114:115], v[166:167] op_sel_hi:[1,0]
	v_exp_f32_e32 v182, v182
	v_exp_f32_e32 v183, v183
	v_exp_f32_e32 v184, v184
	v_exp_f32_e32 v185, v185
	v_exp_f32_e32 v186, v186
	v_exp_f32_e32 v187, v187
	v_exp_f32_e32 v188, v188
	v_exp_f32_e32 v189, v189
	v_pk_add_f32 v[182:183], v[182:183], v[168:169]
	v_pk_add_f32 v[184:185], v[184:185], v[168:169]
	v_pk_add_f32 v[186:187], v[186:187], v[168:169]
	v_pk_add_f32 v[188:189], v[188:189], v[168:169]
	v_rcp_f32_e32 v182, v182
	v_rcp_f32_e32 v183, v183
	v_rcp_f32_e32 v184, v184
	v_rcp_f32_e32 v185, v185
	v_rcp_f32_e32 v186, v186
	v_rcp_f32_e32 v187, v187
	v_rcp_f32_e32 v188, v188
	v_rcp_f32_e32 v189, v189
	s_nop 0
	v_pk_mul_f32 v[116:117], v[116:117], v[182:183]
	v_pk_mul_f32 v[118:119], v[118:119], v[184:185]
	v_pk_mul_f32 v[112:113], v[112:113], v[186:187]
	v_pk_mul_f32 v[114:115], v[114:115], v[188:189]
	v_cvt_pk_bf16_f32 v124, v124, v125
	v_cvt_pk_bf16_f32 v125, v126, v127
	v_cvt_pk_bf16_f32 v126, v120, v121
	v_cvt_pk_bf16_f32 v127, v122, v123
	v_cvt_pk_bf16_f32 v116, v116, v117
	v_cvt_pk_bf16_f32 v117, v118, v119
	v_cvt_pk_bf16_f32 v118, v112, v113
	v_cvt_pk_bf16_f32 v119, v114, v115
	global_store_dwordx4 v[162:163], v[124:127], off
	global_store_dwordx4 v[162:163], v[116:119], off offset:256
	s_waitcnt vmcnt(8)
	v_cvt_f32_u32_e32 v170, v193
	v_cvt_f32_u32_e32 v171, v192
	v_fmamk_f32 v170, v170, 0x4f800000, v171
	v_fmamk_f32 v170, v170, 0x2a800000, v179
	v_rsq_f32_e32 v164, v170
	s_nop 0
	v_pk_mul_f32 v[108:109], v[108:109], v[164:165] op_sel_hi:[1,0]
	v_pk_mul_f32 v[110:111], v[110:111], v[164:165] op_sel_hi:[1,0]
	v_pk_mul_f32 v[104:105], v[104:105], v[164:165] op_sel_hi:[1,0]
	v_pk_mul_f32 v[106:107], v[106:107], v[164:165] op_sel_hi:[1,0]
	v_pk_mul_f32 v[100:101], v[100:101], v[164:165] op_sel_hi:[1,0]
	v_pk_mul_f32 v[102:103], v[102:103], v[164:165] op_sel_hi:[1,0]
	v_pk_mul_f32 v[96:97], v[96:97], v[164:165] op_sel_hi:[1,0]
	v_pk_mul_f32 v[98:99], v[98:99], v[164:165] op_sel_hi:[1,0]
	v_pk_mul_f32 v[182:183], v[108:109], v[166:167] op_sel_hi:[1,0]
	v_pk_mul_f32 v[184:185], v[110:111], v[166:167] op_sel_hi:[1,0]
	v_pk_mul_f32 v[186:187], v[104:105], v[166:167] op_sel_hi:[1,0]
	v_pk_mul_f32 v[188:189], v[106:107], v[166:167] op_sel_hi:[1,0]
	v_exp_f32_e32 v182, v182
	v_exp_f32_e32 v183, v183
	v_exp_f32_e32 v184, v184
	v_exp_f32_e32 v185, v185
	v_exp_f32_e32 v186, v186
	v_exp_f32_e32 v187, v187
	v_exp_f32_e32 v188, v188
	v_exp_f32_e32 v189, v189
	v_pk_add_f32 v[182:183], v[182:183], v[168:169]
	v_pk_add_f32 v[184:185], v[184:185], v[168:169]
	v_pk_add_f32 v[186:187], v[186:187], v[168:169]
	v_pk_add_f32 v[188:189], v[188:189], v[168:169]
	v_rcp_f32_e32 v182, v182
	v_rcp_f32_e32 v183, v183
	v_rcp_f32_e32 v184, v184
	v_rcp_f32_e32 v185, v185
	v_rcp_f32_e32 v186, v186
	v_rcp_f32_e32 v187, v187
	v_rcp_f32_e32 v188, v188
	v_rcp_f32_e32 v189, v189
	s_nop 0
	v_pk_mul_f32 v[108:109], v[108:109], v[182:183]
	v_pk_mul_f32 v[110:111], v[110:111], v[184:185]
	v_pk_mul_f32 v[104:105], v[104:105], v[186:187]
	v_pk_mul_f32 v[106:107], v[106:107], v[188:189]
	v_pk_mul_f32 v[182:183], v[100:101], v[166:167] op_sel_hi:[1,0]
	v_pk_mul_f32 v[184:185], v[102:103], v[166:167] op_sel_hi:[1,0]
	v_pk_mul_f32 v[186:187], v[96:97], v[166:167] op_sel_hi:[1,0]
	v_pk_mul_f32 v[188:189], v[98:99], v[166:167] op_sel_hi:[1,0]
	v_exp_f32_e32 v182, v182
	v_exp_f32_e32 v183, v183
	v_exp_f32_e32 v184, v184
	v_exp_f32_e32 v185, v185
	v_exp_f32_e32 v186, v186
	v_exp_f32_e32 v187, v187
	v_exp_f32_e32 v188, v188
	v_exp_f32_e32 v189, v189
	v_pk_add_f32 v[182:183], v[182:183], v[168:169]
	v_pk_add_f32 v[184:185], v[184:185], v[168:169]
	v_pk_add_f32 v[186:187], v[186:187], v[168:169]
	v_pk_add_f32 v[188:189], v[188:189], v[168:169]
	v_rcp_f32_e32 v182, v182
	v_rcp_f32_e32 v183, v183
	v_rcp_f32_e32 v184, v184
	v_rcp_f32_e32 v185, v185
	v_rcp_f32_e32 v186, v186
	v_rcp_f32_e32 v187, v187
	v_rcp_f32_e32 v188, v188
	v_rcp_f32_e32 v189, v189
	s_nop 0
	v_pk_mul_f32 v[100:101], v[100:101], v[182:183]
	v_pk_mul_f32 v[102:103], v[102:103], v[184:185]
	v_pk_mul_f32 v[96:97], v[96:97], v[186:187]
	v_pk_mul_f32 v[98:99], v[98:99], v[188:189]
	v_cvt_pk_bf16_f32 v108, v108, v109
	v_cvt_pk_bf16_f32 v109, v110, v111
	v_cvt_pk_bf16_f32 v110, v104, v105
	v_cvt_pk_bf16_f32 v111, v106, v107
	v_cvt_pk_bf16_f32 v100, v100, v101
	v_cvt_pk_bf16_f32 v101, v102, v103
	v_cvt_pk_bf16_f32 v102, v96, v97
	v_cvt_pk_bf16_f32 v103, v98, v99
	s_mov_b32 s100, 0x1c000
	v_lshl_add_u64 v[172:173], v[162:163], 0, s[100:101]
	global_store_dwordx4 v[172:173], v[108:111], off
	global_store_dwordx4 v[172:173], v[100:103], off offset:256
	s_waitcnt vmcnt(9)
; __device__ __forceinline__ float ss_scale(const u64* ss, int row) { return __builtin_amdgcn_rsqf((float)ss[row] * (1.f / 4294967296.f / 1024.f) + EPS); }
; __device__ __forceinline__ unsigned pkbf(float lo, float hi) { typedef __bf16 bf2_t __attribute__((ext_vector_type(2))); f32x2 v = {lo, hi}; bf2_t b = __builtin_convertvector(v, bf2_t); return __builtin_bit_cast(unsigned, b); }
; __device__ __forceinline__ float silu_f(float g) { return g * __builtin_amdgcn_rcpf(1.f + __builtin_amdgcn_exp2f(-g * LOG2E)); }
;     __device__ __forceinline__ void operator()(const f32x4 (&acc)[2][2][4][2], const pg8::Unit& u, int wr, int wc, int fr, int fq) const {
;     ...
;         } else {
;             const bool act = (type == 3);
; #pragma unroll
;             for (int ai = 0; ai < 2; ++ai)
; #pragma unroll
;                 for (int m = 0; m < 4; ++m) {
;                     const int row = row0 + ai * 128 + m * 16;
;                     const float s = ss_scale(ss, row);
;                     bf16* op = P + (size_t)row * NIN + cbase + wc * 32 + 8 * fq;
; #pragma unroll
;                     for (int bj = 0; bj < 2; ++bj) {
;                         float v[8];
; #pragma unroll
;                         for (int n = 0; n < 2; ++n)
; #pragma unroll
;                             for (int i = 0; i < 4; ++i) { const float x = acc[ai][bj][m][n][i] * s; v[4 * n + i] = act ? silu_f(x) : x; }
;                         u32x4 w; w.x = pkbf(v[0], v[1]); w.y = pkbf(v[2], v[3]); w.z = pkbf(v[4], v[5]); w.w = pkbf(v[6], v[7]);
;                         *(u32x4*)(op + bj * 128) = w;
;                     }
;                 }
	v_cvt_f32_u32_e32 v170, v195
	v_cvt_f32_u32_e32 v171, v194
	v_fmamk_f32 v170, v170, 0x4f800000, v171
	v_fmamk_f32 v170, v170, 0x2a800000, v179
	v_rsq_f32_e32 v164, v170
	s_nop 0
	v_pk_mul_f32 v[92:93], v[92:93], v[164:165] op_sel_hi:[1,0]
	v_pk_mul_f32 v[94:95], v[94:95], v[164:165] op_sel_hi:[1,0]
	v_pk_mul_f32 v[88:89], v[88:89], v[164:165] op_sel_hi:[1,0]
	v_pk_mul_f32 v[90:91], v[90:91], v[164:165] op_sel_hi:[1,0]
	v_pk_mul_f32 v[84:85], v[84:85], v[164:165] op_sel_hi:[1,0]
	v_pk_mul_f32 v[86:87], v[86:87], v[164:165] op_sel_hi:[1,0]
	v_pk_mul_f32 v[80:81], v[80:81], v[164:165] op_sel_hi:[1,0]
	v_pk_mul_f32 v[82:83], v[82:83], v[164:165] op_sel_hi:[1,0]
	v_pk_mul_f32 v[182:183], v[92:93], v[166:167] op_sel_hi:[1,0]
	v_pk_mul_f32 v[184:185], v[94:95], v[166:167] op_sel_hi:[1,0]
	v_pk_mul_f32 v[186:187], v[88:89], v[166:167] op_sel_hi:[1,0]
	v_pk_mul_f32 v[188:189], v[90:91], v[166:167] op_sel_hi:[1,0]
	v_exp_f32_e32 v182, v182
	v_exp_f32_e32 v183, v183
	v_exp_f32_e32 v184, v184
	v_exp_f32_e32 v185, v185
	v_exp_f32_e32 v186, v186
	v_exp_f32_e32 v187, v187
	v_exp_f32_e32 v188, v188
	v_exp_f32_e32 v189, v189
	v_pk_add_f32 v[182:183], v[182:183], v[168:169]
	v_pk_add_f32 v[184:185], v[184:185], v[168:169]
	v_pk_add_f32 v[186:187], v[186:187], v[168:169]
	v_pk_add_f32 v[188:189], v[188:189], v[168:169]
	v_rcp_f32_e32 v182, v182
	v_rcp_f32_e32 v183, v183
	v_rcp_f32_e32 v184, v184
	v_rcp_f32_e32 v185, v185
	v_rcp_f32_e32 v186, v186
	v_rcp_f32_e32 v187, v187
	v_rcp_f32_e32 v188, v188
	v_rcp_f32_e32 v189, v189
	s_nop 0
	v_pk_mul_f32 v[92:93], v[92:93], v[182:183]
	v_pk_mul_f32 v[94:95], v[94:95], v[184:185]
	v_pk_mul_f32 v[88:89], v[88:89], v[186:187]
	v_pk_mul_f32 v[90:91], v[90:91], v[188:189]
	v_pk_mul_f32 v[182:183], v[84:85], v[166:167] op_sel_hi:[1,0]
	v_pk_mul_f32 v[184:185], v[86:87], v[166:167] op_sel_hi:[1,0]
	v_pk_mul_f32 v[186:187], v[80:81], v[166:167] op_sel_hi:[1,0]
	v_pk_mul_f32 v[188:189], v[82:83], v[166:167] op_sel_hi:[1,0]
	v_exp_f32_e32 v182, v182
	v_exp_f32_e32 v183, v183
	v_exp_f32_e32 v184, v184
	v_exp_f32_e32 v185, v185
	v_exp_f32_e32 v186, v186
	v_exp_f32_e32 v187, v187
	v_exp_f32_e32 v188, v188
	v_exp_f32_e32 v189, v189
	v_pk_add_f32 v[182:183], v[182:183], v[168:169]
	v_pk_add_f32 v[184:185], v[184:185], v[168:169]
	v_pk_add_f32 v[186:187], v[186:187], v[168:169]
	v_pk_add_f32 v[188:189], v[188:189], v[168:169]
	v_rcp_f32_e32 v182, v182
	v_rcp_f32_e32 v183, v183
	v_rcp_f32_e32 v184, v184
	v_rcp_f32_e32 v185, v185
	v_rcp_f32_e32 v186, v186
	v_rcp_f32_e32 v187, v187
	v_rcp_f32_e32 v188, v188
	v_rcp_f32_e32 v189, v189
	s_nop 0
	v_pk_mul_f32 v[84:85], v[84:85], v[182:183]
	v_pk_mul_f32 v[86:87], v[86:87], v[184:185]
	v_pk_mul_f32 v[80:81], v[80:81], v[186:187]
	v_pk_mul_f32 v[82:83], v[82:83], v[188:189]
	v_cvt_pk_bf16_f32 v92, v92, v93
	v_cvt_pk_bf16_f32 v93, v94, v95
	v_cvt_pk_bf16_f32 v94, v88, v89
	v_cvt_pk_bf16_f32 v95, v90, v91
	v_cvt_pk_bf16_f32 v84, v84, v85
	v_cvt_pk_bf16_f32 v85, v86, v87
	v_cvt_pk_bf16_f32 v86, v80, v81
	v_cvt_pk_bf16_f32 v87, v82, v83
	s_mov_b32 s100, 0x38000
	v_lshl_add_u64 v[172:173], v[162:163], 0, s[100:101]
	global_store_dwordx4 v[172:173], v[92:95], off
	global_store_dwordx4 v[172:173], v[84:87], off offset:256
	s_waitcnt vmcnt(10)
	v_cvt_f32_u32_e32 v170, v197
	v_cvt_f32_u32_e32 v171, v196
	v_fmamk_f32 v170, v170, 0x4f800000, v171
	v_fmamk_f32 v170, v170, 0x2a800000, v179
	v_rsq_f32_e32 v164, v170
	s_nop 0
	v_pk_mul_f32 v[76:77], v[76:77], v[164:165] op_sel_hi:[1,0]
	v_pk_mul_f32 v[78:79], v[78:79], v[164:165] op_sel_hi:[1,0]
	v_pk_mul_f32 v[72:73], v[72:73], v[164:165] op_sel_hi:[1,0]
	v_pk_mul_f32 v[74:75], v[74:75], v[164:165] op_sel_hi:[1,0]
	v_pk_mul_f32 v[68:69], v[68:69], v[164:165] op_sel_hi:[1,0]
	v_pk_mul_f32 v[70:71], v[70:71], v[164:165] op_sel_hi:[1,0]
	v_pk_mul_f32 v[64:65], v[64:65], v[164:165] op_sel_hi:[1,0]
	v_pk_mul_f32 v[66:67], v[66:67], v[164:165] op_sel_hi:[1,0]
	v_pk_mul_f32 v[182:183], v[76:77], v[166:167] op_sel_hi:[1,0]
	v_pk_mul_f32 v[184:185], v[78:79], v[166:167] op_sel_hi:[1,0]
	v_pk_mul_f32 v[186:187], v[72:73], v[166:167] op_sel_hi:[1,0]
	v_pk_mul_f32 v[188:189], v[74:75], v[166:167] op_sel_hi:[1,0]
	v_exp_f32_e32 v182, v182
	v_exp_f32_e32 v183, v183
	v_exp_f32_e32 v184, v184
	v_exp_f32_e32 v185, v185
	v_exp_f32_e32 v186, v186
	v_exp_f32_e32 v187, v187
	v_exp_f32_e32 v188, v188
	v_exp_f32_e32 v189, v189
	v_pk_add_f32 v[182:183], v[182:183], v[168:169]
	v_pk_add_f32 v[184:185], v[184:185], v[168:169]
	v_pk_add_f32 v[186:187], v[186:187], v[168:169]
	v_pk_add_f32 v[188:189], v[188:189], v[168:169]
	v_rcp_f32_e32 v182, v182
	v_rcp_f32_e32 v183, v183
	v_rcp_f32_e32 v184, v184
	v_rcp_f32_e32 v185, v185
	v_rcp_f32_e32 v186, v186
	v_rcp_f32_e32 v187, v187
	v_rcp_f32_e32 v188, v188
	v_rcp_f32_e32 v189, v189
	s_nop 0
	v_pk_mul_f32 v[76:77], v[76:77], v[182:183]
	v_pk_mul_f32 v[78:79], v[78:79], v[184:185]
	v_pk_mul_f32 v[72:73], v[72:73], v[186:187]
	v_pk_mul_f32 v[74:75], v[74:75], v[188:189]
	v_pk_mul_f32 v[182:183], v[68:69], v[166:167] op_sel_hi:[1,0]
	v_pk_mul_f32 v[184:185], v[70:71], v[166:167] op_sel_hi:[1,0]
	v_pk_mul_f32 v[186:187], v[64:65], v[166:167] op_sel_hi:[1,0]
	v_pk_mul_f32 v[188:189], v[66:67], v[166:167] op_sel_hi:[1,0]
	v_exp_f32_e32 v182, v182
	v_exp_f32_e32 v183, v183
	v_exp_f32_e32 v184, v184
	v_exp_f32_e32 v185, v185
	v_exp_f32_e32 v186, v186
	v_exp_f32_e32 v187, v187
	v_exp_f32_e32 v188, v188
	v_exp_f32_e32 v189, v189
	v_pk_add_f32 v[182:183], v[182:183], v[168:169]
	v_pk_add_f32 v[184:185], v[184:185], v[168:169]
	v_pk_add_f32 v[186:187], v[186:187], v[168:169]
	v_pk_add_f32 v[188:189], v[188:189], v[168:169]
	v_rcp_f32_e32 v182, v182
	v_rcp_f32_e32 v183, v183
	v_rcp_f32_e32 v184, v184
	v_rcp_f32_e32 v185, v185
	v_rcp_f32_e32 v186, v186
	v_rcp_f32_e32 v187, v187
	v_rcp_f32_e32 v188, v188
	v_rcp_f32_e32 v189, v189
	s_nop 0
	v_pk_mul_f32 v[68:69], v[68:69], v[182:183]
	v_pk_mul_f32 v[70:71], v[70:71], v[184:185]
	v_pk_mul_f32 v[64:65], v[64:65], v[186:187]
	v_pk_mul_f32 v[66:67], v[66:67], v[188:189]
	v_cvt_pk_bf16_f32 v76, v76, v77
	v_cvt_pk_bf16_f32 v77, v78, v79
	v_cvt_pk_bf16_f32 v78, v72, v73
	v_cvt_pk_bf16_f32 v79, v74, v75
	v_cvt_pk_bf16_f32 v68, v68, v69
	v_cvt_pk_bf16_f32 v69, v70, v71
	v_cvt_pk_bf16_f32 v70, v64, v65
	v_cvt_pk_bf16_f32 v71, v66, v67
	s_mov_b32 s100, 0x54000
	v_lshl_add_u64 v[172:173], v[162:163], 0, s[100:101]
	global_store_dwordx4 v[172:173], v[76:79], off
	global_store_dwordx4 v[172:173], v[68:71], off offset:256
	s_waitcnt vmcnt(11)
; __device__ __forceinline__ float ss_scale(const u64* ss, int row) { return __builtin_amdgcn_rsqf((float)ss[row] * (1.f / 4294967296.f / 1024.f) + EPS); }
; __device__ __forceinline__ unsigned pkbf(float lo, float hi) { typedef __bf16 bf2_t __attribute__((ext_vector_type(2))); f32x2 v = {lo, hi}; bf2_t b = __builtin_convertvector(v, bf2_t); return __builtin_bit_cast(unsigned, b); }
; __device__ __forceinline__ float silu_f(float g) { return g * __builtin_amdgcn_rcpf(1.f + __builtin_amdgcn_exp2f(-g * LOG2E)); }
;     __device__ __forceinline__ void operator()(const f32x4 (&acc)[2][2][4][2], const pg8::Unit& u, int wr, int wc, int fr, int fq) const {
;     ...
;         } else {
;             const bool act = (type == 3);
; #pragma unroll
;             for (int ai = 0; ai < 2; ++ai)
; #pragma unroll
;                 for (int m = 0; m < 4; ++m) {
;                     const int row = row0 + ai * 128 + m * 16;
;                     const float s = ss_scale(ss, row);
;                     bf16* op = P + (size_t)row * NIN + cbase + wc * 32 + 8 * fq;
; #pragma unroll
;                     for (int bj = 0; bj < 2; ++bj) {
;                         float v[8];
; #pragma unroll
;                         for (int n = 0; n < 2; ++n)
; #pragma unroll
;                             for (int i = 0; i < 4; ++i) { const float x = acc[ai][bj][m][n][i] * s; v[4 * n + i] = act ? silu_f(x) : x; }
;                         u32x4 w; w.x = pkbf(v[0], v[1]); w.y = pkbf(v[2], v[3]); w.z = pkbf(v[4], v[5]); w.w = pkbf(v[6], v[7]);
;                         *(u32x4*)(op + bj * 128) = w;
;                     }
;                 }
	v_cvt_f32_u32_e32 v170, v201
	v_cvt_f32_u32_e32 v171, v200
	v_fmamk_f32 v170, v170, 0x4f800000, v171
	v_fmamk_f32 v170, v170, 0x2a800000, v179
	v_rsq_f32_e32 v164, v170
	s_nop 0
	v_pk_mul_f32 v[60:61], v[60:61], v[164:165] op_sel_hi:[1,0]
	v_pk_mul_f32 v[62:63], v[62:63], v[164:165] op_sel_hi:[1,0]
	v_pk_mul_f32 v[56:57], v[56:57], v[164:165] op_sel_hi:[1,0]
	v_pk_mul_f32 v[58:59], v[58:59], v[164:165] op_sel_hi:[1,0]
	v_pk_mul_f32 v[52:53], v[52:53], v[164:165] op_sel_hi:[1,0]
	v_pk_mul_f32 v[54:55], v[54:55], v[164:165] op_sel_hi:[1,0]
	v_pk_mul_f32 v[48:49], v[48:49], v[164:165] op_sel_hi:[1,0]
	v_pk_mul_f32 v[50:51], v[50:51], v[164:165] op_sel_hi:[1,0]
	v_pk_mul_f32 v[182:183], v[60:61], v[166:167] op_sel_hi:[1,0]
	v_pk_mul_f32 v[184:185], v[62:63], v[166:167] op_sel_hi:[1,0]
	v_pk_mul_f32 v[186:187], v[56:57], v[166:167] op_sel_hi:[1,0]
	v_pk_mul_f32 v[188:189], v[58:59], v[166:167] op_sel_hi:[1,0]
	v_exp_f32_e32 v182, v182
	v_exp_f32_e32 v183, v183
	v_exp_f32_e32 v184, v184
	v_exp_f32_e32 v185, v185
	v_exp_f32_e32 v186, v186
	v_exp_f32_e32 v187, v187
	v_exp_f32_e32 v188, v188
	v_exp_f32_e32 v189, v189
	v_pk_add_f32 v[182:183], v[182:183], v[168:169]
	v_pk_add_f32 v[184:185], v[184:185], v[168:169]
	v_pk_add_f32 v[186:187], v[186:187], v[168:169]
	v_pk_add_f32 v[188:189], v[188:189], v[168:169]
	v_rcp_f32_e32 v182, v182
	v_rcp_f32_e32 v183, v183
	v_rcp_f32_e32 v184, v184
	v_rcp_f32_e32 v185, v185
	v_rcp_f32_e32 v186, v186
	v_rcp_f32_e32 v187, v187
	v_rcp_f32_e32 v188, v188
	v_rcp_f32_e32 v189, v189
	s_nop 0
	v_pk_mul_f32 v[60:61], v[60:61], v[182:183]
	v_pk_mul_f32 v[62:63], v[62:63], v[184:185]
	v_pk_mul_f32 v[56:57], v[56:57], v[186:187]
	v_pk_mul_f32 v[58:59], v[58:59], v[188:189]
	v_pk_mul_f32 v[182:183], v[52:53], v[166:167] op_sel_hi:[1,0]
	v_pk_mul_f32 v[184:185], v[54:55], v[166:167] op_sel_hi:[1,0]
	v_pk_mul_f32 v[186:187], v[48:49], v[166:167] op_sel_hi:[1,0]
	v_pk_mul_f32 v[188:189], v[50:51], v[166:167] op_sel_hi:[1,0]
	v_exp_f32_e32 v182, v182
	v_exp_f32_e32 v183, v183
	v_exp_f32_e32 v184, v184
	v_exp_f32_e32 v185, v185
	v_exp_f32_e32 v186, v186
	v_exp_f32_e32 v187, v187
	v_exp_f32_e32 v188, v188
	v_exp_f32_e32 v189, v189
	v_pk_add_f32 v[182:183], v[182:183], v[168:169]
	v_pk_add_f32 v[184:185], v[184:185], v[168:169]
	v_pk_add_f32 v[186:187], v[186:187], v[168:169]
	v_pk_add_f32 v[188:189], v[188:189], v[168:169]
	v_rcp_f32_e32 v182, v182
	v_rcp_f32_e32 v183, v183
	v_rcp_f32_e32 v184, v184
	v_rcp_f32_e32 v185, v185
	v_rcp_f32_e32 v186, v186
	v_rcp_f32_e32 v187, v187
	v_rcp_f32_e32 v188, v188
	v_rcp_f32_e32 v189, v189
	s_nop 0
	v_pk_mul_f32 v[52:53], v[52:53], v[182:183]
	v_pk_mul_f32 v[54:55], v[54:55], v[184:185]
	v_pk_mul_f32 v[48:49], v[48:49], v[186:187]
	v_pk_mul_f32 v[50:51], v[50:51], v[188:189]
	v_cvt_pk_bf16_f32 v60, v60, v61
	v_cvt_pk_bf16_f32 v61, v62, v63
	v_cvt_pk_bf16_f32 v62, v56, v57
	v_cvt_pk_bf16_f32 v63, v58, v59
	v_cvt_pk_bf16_f32 v52, v52, v53
	v_cvt_pk_bf16_f32 v53, v54, v55
	v_cvt_pk_bf16_f32 v54, v48, v49
	v_cvt_pk_bf16_f32 v55, v50, v51
	s_mov_b32 s100, 0xe0000
	v_lshl_add_u64 v[172:173], v[162:163], 0, s[100:101]
	global_store_dwordx4 v[172:173], v[60:63], off
	global_store_dwordx4 v[172:173], v[52:55], off offset:256
	s_waitcnt vmcnt(12)
	v_cvt_f32_u32_e32 v170, v203
	v_cvt_f32_u32_e32 v171, v202
	v_fmamk_f32 v170, v170, 0x4f800000, v171
	v_fmamk_f32 v170, v170, 0x2a800000, v179
	v_rsq_f32_e32 v164, v170
	s_nop 0
	v_pk_mul_f32 v[44:45], v[44:45], v[164:165] op_sel_hi:[1,0]
	v_pk_mul_f32 v[46:47], v[46:47], v[164:165] op_sel_hi:[1,0]
	v_pk_mul_f32 v[40:41], v[40:41], v[164:165] op_sel_hi:[1,0]
	v_pk_mul_f32 v[42:43], v[42:43], v[164:165] op_sel_hi:[1,0]
	v_pk_mul_f32 v[36:37], v[36:37], v[164:165] op_sel_hi:[1,0]
	v_pk_mul_f32 v[38:39], v[38:39], v[164:165] op_sel_hi:[1,0]
	v_pk_mul_f32 v[32:33], v[32:33], v[164:165] op_sel_hi:[1,0]
	v_pk_mul_f32 v[34:35], v[34:35], v[164:165] op_sel_hi:[1,0]
	v_pk_mul_f32 v[182:183], v[44:45], v[166:167] op_sel_hi:[1,0]
	v_pk_mul_f32 v[184:185], v[46:47], v[166:167] op_sel_hi:[1,0]
	v_pk_mul_f32 v[186:187], v[40:41], v[166:167] op_sel_hi:[1,0]
	v_pk_mul_f32 v[188:189], v[42:43], v[166:167] op_sel_hi:[1,0]
	v_exp_f32_e32 v182, v182
	v_exp_f32_e32 v183, v183
	v_exp_f32_e32 v184, v184
	v_exp_f32_e32 v185, v185
	v_exp_f32_e32 v186, v186
	v_exp_f32_e32 v187, v187
	v_exp_f32_e32 v188, v188
	v_exp_f32_e32 v189, v189
	v_pk_add_f32 v[182:183], v[182:183], v[168:169]
	v_pk_add_f32 v[184:185], v[184:185], v[168:169]
	v_pk_add_f32 v[186:187], v[186:187], v[168:169]
	v_pk_add_f32 v[188:189], v[188:189], v[168:169]
	v_rcp_f32_e32 v182, v182
	v_rcp_f32_e32 v183, v183
	v_rcp_f32_e32 v184, v184
	v_rcp_f32_e32 v185, v185
	v_rcp_f32_e32 v186, v186
	v_rcp_f32_e32 v187, v187
	v_rcp_f32_e32 v188, v188
	v_rcp_f32_e32 v189, v189
	s_nop 0
	v_pk_mul_f32 v[44:45], v[44:45], v[182:183]
	v_pk_mul_f32 v[46:47], v[46:47], v[184:185]
	v_pk_mul_f32 v[40:41], v[40:41], v[186:187]
	v_pk_mul_f32 v[42:43], v[42:43], v[188:189]
	v_pk_mul_f32 v[182:183], v[36:37], v[166:167] op_sel_hi:[1,0]
	v_pk_mul_f32 v[184:185], v[38:39], v[166:167] op_sel_hi:[1,0]
	v_pk_mul_f32 v[186:187], v[32:33], v[166:167] op_sel_hi:[1,0]
	v_pk_mul_f32 v[188:189], v[34:35], v[166:167] op_sel_hi:[1,0]
	v_exp_f32_e32 v182, v182
	v_exp_f32_e32 v183, v183
	v_exp_f32_e32 v184, v184
	v_exp_f32_e32 v185, v185
	v_exp_f32_e32 v186, v186
	v_exp_f32_e32 v187, v187
	v_exp_f32_e32 v188, v188
	v_exp_f32_e32 v189, v189
	v_pk_add_f32 v[182:183], v[182:183], v[168:169]
	v_pk_add_f32 v[184:185], v[184:185], v[168:169]
	v_pk_add_f32 v[186:187], v[186:187], v[168:169]
	v_pk_add_f32 v[188:189], v[188:189], v[168:169]
	v_rcp_f32_e32 v182, v182
	v_rcp_f32_e32 v183, v183
	v_rcp_f32_e32 v184, v184
	v_rcp_f32_e32 v185, v185
	v_rcp_f32_e32 v186, v186
	v_rcp_f32_e32 v187, v187
	v_rcp_f32_e32 v188, v188
	v_rcp_f32_e32 v189, v189
	s_nop 0
	v_pk_mul_f32 v[36:37], v[36:37], v[182:183]
	v_pk_mul_f32 v[38:39], v[38:39], v[184:185]
	v_pk_mul_f32 v[32:33], v[32:33], v[186:187]
	v_pk_mul_f32 v[34:35], v[34:35], v[188:189]
	v_cvt_pk_bf16_f32 v44, v44, v45
	v_cvt_pk_bf16_f32 v45, v46, v47
	v_cvt_pk_bf16_f32 v46, v40, v41
	v_cvt_pk_bf16_f32 v47, v42, v43
	v_cvt_pk_bf16_f32 v36, v36, v37
	v_cvt_pk_bf16_f32 v37, v38, v39
	v_cvt_pk_bf16_f32 v38, v32, v33
	v_cvt_pk_bf16_f32 v39, v34, v35
	s_mov_b32 s100, 0xfc000
	v_lshl_add_u64 v[172:173], v[162:163], 0, s[100:101]
	global_store_dwordx4 v[172:173], v[44:47], off
	global_store_dwordx4 v[172:173], v[36:39], off offset:256
	s_waitcnt vmcnt(13)
; __device__ __forceinline__ float ss_scale(const u64* ss, int row) { return __builtin_amdgcn_rsqf((float)ss[row] * (1.f / 4294967296.f / 1024.f) + EPS); }
; __device__ __forceinline__ unsigned pkbf(float lo, float hi) { typedef __bf16 bf2_t __attribute__((ext_vector_type(2))); f32x2 v = {lo, hi}; bf2_t b = __builtin_convertvector(v, bf2_t); return __builtin_bit_cast(unsigned, b); }
; __device__ __forceinline__ float silu_f(float g) { return g * __builtin_amdgcn_rcpf(1.f + __builtin_amdgcn_exp2f(-g * LOG2E)); }
;     __device__ __forceinline__ void operator()(const f32x4 (&acc)[2][2][4][2], const pg8::Unit& u, int wr, int wc, int fr, int fq) const {
;     ...
;         } else {
;             const bool act = (type == 3);
; #pragma unroll
;             for (int ai = 0; ai < 2; ++ai)
; #pragma unroll
;                 for (int m = 0; m < 4; ++m) {
;                     const int row = row0 + ai * 128 + m * 16;
;                     const float s = ss_scale(ss, row);
;                     bf16* op = P + (size_t)row * NIN + cbase + wc * 32 + 8 * fq;
; #pragma unroll
;                     for (int bj = 0; bj < 2; ++bj) {
;                         float v[8];
; #pragma unroll
;                         for (int n = 0; n < 2; ++n)
; #pragma unroll
;                             for (int i = 0; i < 4; ++i) { const float x = acc[ai][bj][m][n][i] * s; v[4 * n + i] = act ? silu_f(x) : x; }
;                         u32x4 w; w.x = pkbf(v[0], v[1]); w.y = pkbf(v[2], v[3]); w.z = pkbf(v[4], v[5]); w.w = pkbf(v[6], v[7]);
;                         *(u32x4*)(op + bj * 128) = w;
;                     }
;                 }
	v_cvt_f32_u32_e32 v170, v205
	v_cvt_f32_u32_e32 v171, v204
	v_fmamk_f32 v170, v170, 0x4f800000, v171
	v_fmamk_f32 v170, v170, 0x2a800000, v179
	v_rsq_f32_e32 v164, v170
	s_nop 0
	v_pk_mul_f32 v[28:29], v[28:29], v[164:165] op_sel_hi:[1,0]
	v_pk_mul_f32 v[30:31], v[30:31], v[164:165] op_sel_hi:[1,0]
	v_pk_mul_f32 v[24:25], v[24:25], v[164:165] op_sel_hi:[1,0]
	v_pk_mul_f32 v[26:27], v[26:27], v[164:165] op_sel_hi:[1,0]
	v_pk_mul_f32 v[20:21], v[20:21], v[164:165] op_sel_hi:[1,0]
	v_pk_mul_f32 v[22:23], v[22:23], v[164:165] op_sel_hi:[1,0]
	v_pk_mul_f32 v[16:17], v[16:17], v[164:165] op_sel_hi:[1,0]
	v_pk_mul_f32 v[18:19], v[18:19], v[164:165] op_sel_hi:[1,0]
	v_pk_mul_f32 v[182:183], v[28:29], v[166:167] op_sel_hi:[1,0]
	v_pk_mul_f32 v[184:185], v[30:31], v[166:167] op_sel_hi:[1,0]
	v_pk_mul_f32 v[186:187], v[24:25], v[166:167] op_sel_hi:[1,0]
	v_pk_mul_f32 v[188:189], v[26:27], v[166:167] op_sel_hi:[1,0]
	v_exp_f32_e32 v182, v182
	v_exp_f32_e32 v183, v183
	v_exp_f32_e32 v184, v184
	v_exp_f32_e32 v185, v185
	v_exp_f32_e32 v186, v186
	v_exp_f32_e32 v187, v187
	v_exp_f32_e32 v188, v188
	v_exp_f32_e32 v189, v189
	v_pk_add_f32 v[182:183], v[182:183], v[168:169]
	v_pk_add_f32 v[184:185], v[184:185], v[168:169]
	v_pk_add_f32 v[186:187], v[186:187], v[168:169]
	v_pk_add_f32 v[188:189], v[188:189], v[168:169]
	v_rcp_f32_e32 v182, v182
	v_rcp_f32_e32 v183, v183
	v_rcp_f32_e32 v184, v184
	v_rcp_f32_e32 v185, v185
	v_rcp_f32_e32 v186, v186
	v_rcp_f32_e32 v187, v187
	v_rcp_f32_e32 v188, v188
	v_rcp_f32_e32 v189, v189
	s_nop 0
	v_pk_mul_f32 v[28:29], v[28:29], v[182:183]
	v_pk_mul_f32 v[30:31], v[30:31], v[184:185]
	v_pk_mul_f32 v[24:25], v[24:25], v[186:187]
	v_pk_mul_f32 v[26:27], v[26:27], v[188:189]
	v_pk_mul_f32 v[182:183], v[20:21], v[166:167] op_sel_hi:[1,0]
	v_pk_mul_f32 v[184:185], v[22:23], v[166:167] op_sel_hi:[1,0]
	v_pk_mul_f32 v[186:187], v[16:17], v[166:167] op_sel_hi:[1,0]
	v_pk_mul_f32 v[188:189], v[18:19], v[166:167] op_sel_hi:[1,0]
	v_exp_f32_e32 v182, v182
	v_exp_f32_e32 v183, v183
	v_exp_f32_e32 v184, v184
	v_exp_f32_e32 v185, v185
	v_exp_f32_e32 v186, v186
	v_exp_f32_e32 v187, v187
	v_exp_f32_e32 v188, v188
	v_exp_f32_e32 v189, v189
	v_pk_add_f32 v[182:183], v[182:183], v[168:169]
	v_pk_add_f32 v[184:185], v[184:185], v[168:169]
	v_pk_add_f32 v[186:187], v[186:187], v[168:169]
	v_pk_add_f32 v[188:189], v[188:189], v[168:169]
	v_rcp_f32_e32 v182, v182
	v_rcp_f32_e32 v183, v183
	v_rcp_f32_e32 v184, v184
	v_rcp_f32_e32 v185, v185
	v_rcp_f32_e32 v186, v186
	v_rcp_f32_e32 v187, v187
	v_rcp_f32_e32 v188, v188
	v_rcp_f32_e32 v189, v189
	s_nop 0
	v_pk_mul_f32 v[20:21], v[20:21], v[182:183]
	v_pk_mul_f32 v[22:23], v[22:23], v[184:185]
	v_pk_mul_f32 v[16:17], v[16:17], v[186:187]
	v_pk_mul_f32 v[18:19], v[18:19], v[188:189]
	v_cvt_pk_bf16_f32 v28, v28, v29
	v_cvt_pk_bf16_f32 v29, v30, v31
	v_cvt_pk_bf16_f32 v30, v24, v25
	v_cvt_pk_bf16_f32 v31, v26, v27
	v_cvt_pk_bf16_f32 v20, v20, v21
	v_cvt_pk_bf16_f32 v21, v22, v23
	v_cvt_pk_bf16_f32 v22, v16, v17
	v_cvt_pk_bf16_f32 v23, v18, v19
	s_mov_b32 s100, 0x118000
	v_lshl_add_u64 v[172:173], v[162:163], 0, s[100:101]
	global_store_dwordx4 v[172:173], v[28:31], off
	global_store_dwordx4 v[172:173], v[20:23], off offset:256
	s_waitcnt vmcnt(14)
	v_cvt_f32_u32_e32 v170, v207
	v_cvt_f32_u32_e32 v171, v206
	v_fmamk_f32 v170, v170, 0x4f800000, v171
	v_fmamk_f32 v170, v170, 0x2a800000, v179
	v_rsq_f32_e32 v164, v170
	s_nop 0
	v_pk_mul_f32 v[12:13], v[12:13], v[164:165] op_sel_hi:[1,0]
	v_pk_mul_f32 v[14:15], v[14:15], v[164:165] op_sel_hi:[1,0]
	v_pk_mul_f32 v[8:9], v[8:9], v[164:165] op_sel_hi:[1,0]
	v_pk_mul_f32 v[10:11], v[10:11], v[164:165] op_sel_hi:[1,0]
	v_pk_mul_f32 v[4:5], v[4:5], v[164:165] op_sel_hi:[1,0]
	v_pk_mul_f32 v[6:7], v[6:7], v[164:165] op_sel_hi:[1,0]
	v_pk_mul_f32 v[0:1], v[0:1], v[164:165] op_sel_hi:[1,0]
	v_pk_mul_f32 v[2:3], v[2:3], v[164:165] op_sel_hi:[1,0]
	v_pk_mul_f32 v[182:183], v[12:13], v[166:167] op_sel_hi:[1,0]
	v_pk_mul_f32 v[184:185], v[14:15], v[166:167] op_sel_hi:[1,0]
	v_pk_mul_f32 v[186:187], v[8:9], v[166:167] op_sel_hi:[1,0]
	v_pk_mul_f32 v[188:189], v[10:11], v[166:167] op_sel_hi:[1,0]
	v_exp_f32_e32 v182, v182
	v_exp_f32_e32 v183, v183
	v_exp_f32_e32 v184, v184
	v_exp_f32_e32 v185, v185
	v_exp_f32_e32 v186, v186
	v_exp_f32_e32 v187, v187
	v_exp_f32_e32 v188, v188
	v_exp_f32_e32 v189, v189
	v_pk_add_f32 v[182:183], v[182:183], v[168:169]
	v_pk_add_f32 v[184:185], v[184:185], v[168:169]
	v_pk_add_f32 v[186:187], v[186:187], v[168:169]
	v_pk_add_f32 v[188:189], v[188:189], v[168:169]
	v_rcp_f32_e32 v182, v182
	v_rcp_f32_e32 v183, v183
	v_rcp_f32_e32 v184, v184
	v_rcp_f32_e32 v185, v185
	v_rcp_f32_e32 v186, v186
	v_rcp_f32_e32 v187, v187
	v_rcp_f32_e32 v188, v188
	v_rcp_f32_e32 v189, v189
	s_nop 0
	v_pk_mul_f32 v[12:13], v[12:13], v[182:183]
	v_pk_mul_f32 v[14:15], v[14:15], v[184:185]
	v_pk_mul_f32 v[8:9], v[8:9], v[186:187]
	v_pk_mul_f32 v[10:11], v[10:11], v[188:189]
	v_pk_mul_f32 v[182:183], v[4:5], v[166:167] op_sel_hi:[1,0]
	v_pk_mul_f32 v[184:185], v[6:7], v[166:167] op_sel_hi:[1,0]
	v_pk_mul_f32 v[186:187], v[0:1], v[166:167] op_sel_hi:[1,0]
	v_pk_mul_f32 v[188:189], v[2:3], v[166:167] op_sel_hi:[1,0]
	v_exp_f32_e32 v182, v182
	v_exp_f32_e32 v183, v183
	v_exp_f32_e32 v184, v184
	v_exp_f32_e32 v185, v185
	v_exp_f32_e32 v186, v186
	v_exp_f32_e32 v187, v187
	v_exp_f32_e32 v188, v188
	v_exp_f32_e32 v189, v189
	v_pk_add_f32 v[182:183], v[182:183], v[168:169]
	v_pk_add_f32 v[184:185], v[184:185], v[168:169]
	v_pk_add_f32 v[186:187], v[186:187], v[168:169]
	v_pk_add_f32 v[188:189], v[188:189], v[168:169]
	v_rcp_f32_e32 v182, v182
	v_rcp_f32_e32 v183, v183
	v_rcp_f32_e32 v184, v184
	v_rcp_f32_e32 v185, v185
	v_rcp_f32_e32 v186, v186
	v_rcp_f32_e32 v187, v187
	v_rcp_f32_e32 v188, v188
	v_rcp_f32_e32 v189, v189
	s_nop 0
	v_pk_mul_f32 v[4:5], v[4:5], v[182:183]
	v_pk_mul_f32 v[6:7], v[6:7], v[184:185]
	v_pk_mul_f32 v[0:1], v[0:1], v[186:187]
	v_pk_mul_f32 v[2:3], v[2:3], v[188:189]
	v_cvt_pk_bf16_f32 v12, v12, v13
	v_cvt_pk_bf16_f32 v13, v14, v15
	v_cvt_pk_bf16_f32 v14, v8, v9
	v_cvt_pk_bf16_f32 v15, v10, v11
	v_cvt_pk_bf16_f32 v4, v4, v5
	v_cvt_pk_bf16_f32 v5, v6, v7
	v_cvt_pk_bf16_f32 v6, v0, v1
	v_cvt_pk_bf16_f32 v7, v2, v3
	s_mov_b32 s100, 0x134000
	v_lshl_add_u64 v[172:173], v[162:163], 0, s[100:101]
	global_store_dwordx4 v[172:173], v[12:15], off
	global_store_dwordx4 v[172:173], v[4:7], off offset:256
.Lpl_end_l0:
	s_mov_b64 s[34:35], 0
